# attention phase: one static s_setprio 1 for waves 4..7 for the whole phase (reset at phase end), on top of ragged-round overlap
# speedup vs baseline: 1.0051x; 1.0051x over previous
; #define LAS __attribute__((address_space(3)))
; template <int DH, bool IS_A> ...
;     ...
;     const int i = i0 + c16; const int jmin = max(i + (IS_A ? 1 : 0), jlo), jmax = i + 128;
;     float mx = -INFINITY;
; #pragma unroll
;     for (int T = 0; T < 9; ++T)
; #pragma unroll
;         for (int r = 0; r < 4; ++r) { const int j = i0 + 16 * T + 4 * g + r; const bool ok = (j >= jmin) && (j <= jmax); const float v = ok ? s[T][r] : -INFINITY; s[T][r] = v; mx = fmaxf(mx, v); }
; __global__ void __launch_bounds__(512, 2) hybrid_fwd(Args a) {
;     ...
;         constexpr int N_A = 256, N_B = 1536;
;         const bool xmap = (G % 8 == 0) && (N_A % 8 == 0) && (N_B % 8 == 0);
;         const int xcd = bx & 7, jx = bx >> 3, perx = G >> 3;
;         for (int i0 = bx; i0 < N_A + N_B; i0 += G) {
;             int it = i0;
;             if (xmap) { const int k = i0 / G;
;                 if (i0 < N_A) it = xcd * (N_A / 8) + k * perx + jx;
;                 else { const int kb = (i0 - N_A) / G; it = N_A + xcd * (N_B / 8) + kb * perx + jx; } }
;             __syncthreads();
;             if (it < N_A) {
;                 const int kvh = it & 1, b = it >> 1;
;                 LAS unsigned char* Kl = lds; LAS unsigned char* Vl = lds + 256 * 160;
;                 const int jlo = (b == 0) ? 128 : 0;
;                 load_kv<64>(Kl, Vl, H + OFF_KA + kvh * 64, H + OFF_VA + kvh * 64, (long)(b - 1) * 128, 1, jlo, tid);
;                 __syncthreads();
;                 const int head = kvh * 8 + wave; const float sink2 = a.sinks[head] * LOG2E;
;                 const int g4 = lane >> 4;
;                 bf16x8 qn[2]; u32x2 gn[4];
.LBB0_301:
	s_or_b64 exec, exec, s[0:1]
	v_readfirstlane_b32 s100, v160
	s_cmp_lt_u32 s100, 0x100
	s_cbranch_scc1 .Lp2prio_skip
	s_setprio 1
.Lp2prio_skip:
	s_add_u32 s0, s90, 0x8800000
	s_addc_u32 s1, s91, 0
	s_add_u32 s94, s88, 0x2000000
	v_writelane_b32 v242, s0, 6
	s_addc_u32 s95, s89, 0
	v_cmp_eq_u32_e64 s[60:61], 0, v0
	v_writelane_b32 v242, s1, 7
	s_add_u32 s0, s88, 0x3800000
	s_addc_u32 s1, s89, 0
	s_and_b32 s59, s2, 7
	s_cmpk_gt_i32 s2, 0x6ff
	v_lshlrev_b32_e32 v145, 3, v160
	v_lshlrev_b32_e32 v109, 4, v160
	v_and_b32_e32 v156, 15, v160
	v_lshrrev_b32_e32 v131, 1, v160
	v_bfe_u32 v111, v160, 2, 2
	v_lshrrev_b32_e32 v108, 3, v160
	v_lshrrev_b32_e32 v139, 4, v192
	v_bfe_u32 v161, v160, 4, 2
	v_mbcnt_lo_u32_b32 v186, -1, 0
	s_barrier
	s_cbranch_scc1 .LBB0_340
	v_writelane_b32 v242, s72, 8
	s_ashr_i32 s4, s2, 3
	v_writelane_b32 v242, s4, 9
	s_ashr_i32 s4, s92, 3
	v_writelane_b32 v242, s4, 10
	s_mul_i32 s4, s59, 0xc0
	s_addk_i32 s4, 0x100
	v_writelane_b32 v242, s4, 11
	v_writelane_b32 v242, s59, 12
	s_lshl_b32 s4, s59, 5
	v_writelane_b32 v242, s4, 13
	s_add_u32 s4, s90, 0x9001e00
	s_addc_u32 s5, s91, 0
	s_add_u32 s8, s90, 0x9002a00
	v_readlane_b32 s12, v242, 0
	s_addc_u32 s9, s91, 0
	s_lshl_b32 s12, s12, 4
	v_lshrrev_b32_e32 v6, 2, v160
	v_or_b32_e32 v174, s12, v156
	v_and_b32_e32 v128, 12, v6
	v_add_u32_e32 v5, 0x80, v174
	v_or_b32_e32 v175, s12, v128
	v_cmp_le_u32_e64 s[12:13], v175, v5
	v_or_b32_e32 v177, 2, v175
	v_or_b32_e32 v178, 3, v175
	v_writelane_b32 v242, s12, 14
	v_add_u32_e32 v179, 16, v175
	v_add_u32_e32 v180, 17, v175
	v_writelane_b32 v242, s13, 15
	v_cmp_lt_u32_e64 s[12:13], v175, v5
	v_add_u32_e32 v181, 18, v175
	v_add_u32_e32 v182, 19, v175
	v_writelane_b32 v242, s12, 16
	v_add_u32_e32 v183, 32, v175
	v_add_u32_e32 v0, 0xa00, v160
	v_writelane_b32 v242, s13, 17
	v_cmp_le_u32_e64 s[12:13], v177, v5
	v_add_u32_e32 v184, 33, v175
	v_add_u32_e32 v185, 34, v175
	v_writelane_b32 v242, s12, 18
	v_add_u32_e32 v187, 35, v175
	v_add_u32_e32 v188, 48, v175
	v_writelane_b32 v242, s13, 19
	v_cmp_le_u32_e64 s[12:13], v178, v5
	v_add_u32_e32 v189, 49, v175
	v_add_u32_e32 v190, 50, v175
	v_writelane_b32 v242, s12, 20
	v_add_u32_e32 v191, 51, v175
	v_add_u32_e32 v193, 64, v175
	v_writelane_b32 v242, s13, 21
	v_cmp_le_u32_e64 s[12:13], v179, v5
	v_add_u32_e32 v194, 0x41, v175
	v_add_u32_e32 v195, 0x42, v175
	v_writelane_b32 v242, s12, 22
	v_add_u32_e32 v196, 0x43, v175
	v_add_u32_e32 v197, 0x50, v175
	v_writelane_b32 v242, s13, 23
	v_cmp_le_u32_e64 s[12:13], v180, v5
	v_add_u32_e32 v198, 0x51, v175
	v_add_u32_e32 v199, 0x52, v175
	v_writelane_b32 v242, s12, 24
	v_add_u32_e32 v200, 0x53, v175
	v_add_u32_e32 v201, 0x60, v175
	v_writelane_b32 v242, s13, 25
	v_cmp_le_u32_e64 s[12:13], v181, v5
	v_add_u32_e32 v202, 0x61, v175
	v_add_u32_e32 v203, 0x62, v175
	v_writelane_b32 v242, s12, 26
	v_add_u32_e32 v204, 0x63, v175
	v_add_u32_e32 v205, 0x70, v175
	v_writelane_b32 v242, s13, 27
	v_cmp_le_u32_e64 s[12:13], v182, v5
	v_add_u32_e32 v206, 0x71, v175
	v_add_u32_e32 v207, 0x72, v175
	v_writelane_b32 v242, s12, 28
	v_add_u32_e32 v208, 0x73, v175
	v_add_u32_e32 v6, 0x80, v175
	v_writelane_b32 v242, s13, 29
	v_cmp_le_u32_e64 s[12:13], v183, v5
	v_add_u32_e32 v209, 0x81, v175
	v_add_u32_e32 v210, 0x82, v175
	v_writelane_b32 v242, s12, 30
	v_add_u32_e32 v211, 0x83, v175
	v_lshrrev_b32_e32 v122, 4, v0
	v_add_u32_e32 v0, 0xe00, v160
	s_movk_i32 s11, 0x120
	v_writelane_b32 v242, s13, 31
	v_cmp_le_u32_e64 s[12:13], v184, v5
	v_cmp_le_u32_e64 s[28:29], v185, v5
	v_cmp_le_u32_e64 s[30:31], v187, v5
	v_cmp_le_u32_e64 s[34:35], v188, v5
	v_cmp_le_u32_e64 s[36:37], v189, v5
	v_cmp_le_u32_e64 s[38:39], v190, v5
	v_cmp_le_u32_e64 s[40:41], v191, v5
	v_cmp_le_u32_e64 s[42:43], v193, v5
	v_cmp_le_u32_e64 s[44:45], v194, v5
	v_cmp_le_u32_e64 s[46:47], v195, v5
	v_cmp_le_u32_e64 s[48:49], v196, v5
	v_cmp_le_u32_e64 s[50:51], v197, v5
	v_cmp_le_u32_e64 s[52:53], v198, v5
	v_cmp_le_u32_e64 s[54:55], v199, v5
	v_cmp_le_u32_e64 s[56:57], v200, v5
	v_cmp_le_u32_e64 s[58:59], v201, v5
	v_cmp_le_u32_e64 s[26:27], v202, v5
	v_cmp_le_u32_e64 s[62:63], v203, v5
	v_cmp_le_u32_e64 s[64:65], v204, v5
	v_cmp_le_u32_e64 s[66:67], v205, v5
	v_cmp_le_u32_e64 s[68:69], v206, v5
	v_cmp_le_u32_e64 s[24:25], v207, v5
	v_cmp_le_u32_e64 s[72:73], v208, v5
	v_cmp_le_u32_e32 vcc, v174, v6
	v_cmp_le_u32_e64 s[74:75], v128, v156
	v_cmp_le_u32_e64 s[78:79], v209, v5
	v_cmp_le_u32_e64 s[80:81], v210, v5
	v_cmp_le_u32_e64 s[82:83], v211, v5
	v_or_b32_e32 v5, v175, v111
	v_lshrrev_b32_e32 v126, 4, v0
	v_and_b32_e32 v0, 0xf0, v109
	s_add_i32 s10, 0, 0x12000
	v_and_b32_e32 v4, 48, v160
	s_and_b64 s[76:77], vcc, s[74:75]
	v_mul_lo_u32 v5, v5, s11
	v_and_b32_e32 v6, 24, v145
	v_mul_u32_u24_e32 v9, 0xa0, v156
	v_add_u32_e32 v1, 0x200, v160
	v_add_u32_e32 v2, 0x600, v160
	v_add_u32_e32 v168, s10, v0
	v_add3_u32 v212, s10, v5, v6
	s_add_u32 s10, s90, 0x9000800
	v_add3_u32 v213, v9, v4, 0
	v_mul_u32_u24_e32 v9, 0xa0, v111
	s_movk_i32 s14, 0x280
	v_mov_b32_e32 v8, 0
	v_lshrrev_b32_e32 v114, 4, v1
	v_mul_lo_u32 v3, v174, s11
	v_writelane_b32 v242, s12, 32
	s_addc_u32 s11, s91, 0
	v_lshrrev_b32_e32 v132, 3, v1
	v_lshrrev_b32_e32 v136, 3, v2
	v_and_b32_e32 v1, 0x70, v109
	v_mad_u32_u24 v9, v161, s14, v9
	v_lshrrev_b32_e32 v112, 4, v160
	v_lshrrev_b32_e32 v118, 4, v2
	v_add_u32_e32 v163, 0, v0
	v_and_b32_e32 v0, 24, v131
	v_add_u32_e32 v3, 0, v3
	v_writelane_b32 v242, s13, 33
	v_mov_b32_e32 v129, v8
	s_add_u32 s12, s90, 0x9000900
	v_add_u32_e32 v1, 0, v1
	v_mul_u32_u24_e32 v2, 0xa0, v108
	v_mul_u32_u24_e32 v5, 0xa0, v132
	v_mul_u32_u24_e32 v7, 0xa0, v136
	v_or_b32_e32 v6, v9, v6
	v_and_b32_e32 v110, 0x78, v145
	v_mov_b32_e32 v113, v8
	v_mov_b32_e32 v115, v8
	v_or_b32_e32 v116, 64, v112
	v_mov_b32_e32 v117, v8
	s_movk_i32 s18, 0x600
	v_mov_b32_e32 v119, v8
	v_or_b32_e32 v120, 0x80, v112
	v_mov_b32_e32 v121, v8
	v_mov_b32_e32 v123, v8
	v_or_b32_e32 v124, 0xc0, v112
	v_mov_b32_e32 v125, v8
	v_mov_b32_e32 v127, v8
	v_mul_u32_u24_e32 v169, 0x120, v112
	v_mul_u32_u24_e32 v170, 0x120, v114
	v_mul_u32_u24_e32 v171, 0x120, v118
	v_mul_u32_u24_e32 v172, 0x120, v122
	v_mul_u32_u24_e32 v173, 0x120, v126
	v_or_b32_e32 v176, 1, v175
	v_cmp_gt_u32_e64 s[84:85], 16, v192
	s_addc_u32 s13, s91, 0
	v_and_b32_e32 v130, 56, v145
	v_mov_b32_e32 v133, v8
	v_or_b32_e32 v134, 0x80, v108
	v_mov_b32_e32 v135, v8
	v_mov_b32_e32 v137, v8
	v_mov_b32_e32 v157, v8
	v_lshlrev_b32_e32 v138, 3, v139
	v_lshlrev_b32_e32 v140, 2, v139
	v_mov_b32_e32 v141, v8
	v_lshl_add_u64 v[142:143], s[94:95], 0, v[128:129]
	v_add_u32_e32 v214, 0, v6
	v_lshlrev_b32_e32 v144, 2, v161
	s_movk_i32 s19, 0x2d00
	s_movk_i32 s20, 0x5a00
	v_lshlrev_b32_e32 v146, 1, v0
	v_add_u32_e32 v215, v3, v4
	s_mov_b32 s21, 0xff800000
	v_add_u32_e32 v216, v1, v2
	v_add_u32_e32 v217, v1, v5
	v_add_u32_e32 v218, v1, v7
	v_mov_b32_e32 v219, 0x80
	v_mov_b32_e32 v220, 0xff800000
	v_mbcnt_hi_u32_b32 v221, -1, v186
	s_mov_b32 s22, s2
	s_branch .LBB0_304

; __device__ __forceinline__ void own_barrier(unsigned* cnt, unsigned G) {
;     asm volatile("s_waitcnt vmcnt(0) lgkmcnt(0)" ::: "memory");
;     __syncthreads();
;     if (threadIdx.x == 0) {
;         __builtin_amdgcn_fence(__ATOMIC_RELEASE, "agent"); asm volatile("s_waitcnt vmcnt(0)" ::: "memory");
;         unsigned target;
;         if ((G & 7u) == 0u) { target = 8u;
;             const unsigned old = __hip_atomic_fetch_add(cnt + 64 * (1 + (blockIdx.x & 7)), 1u, __ATOMIC_RELAXED, __HIP_MEMORY_SCOPE_AGENT);
;             if (old + 1u == (G >> 3)) __hip_atomic_fetch_add(cnt, 1u, __ATOMIC_RELAXED, __HIP_MEMORY_SCOPE_AGENT); }
;         else { target = G; __hip_atomic_fetch_add(cnt, 1u, __ATOMIC_RELAXED, __HIP_MEMORY_SCOPE_AGENT); }
;         unsigned spins = 0;
;         while (__hip_atomic_load(cnt, __ATOMIC_RELAXED, __HIP_MEMORY_SCOPE_AGENT) < target && ++spins < (1u << 22)) __builtin_amdgcn_s_sleep(1);
;         __builtin_amdgcn_fence(__ATOMIC_ACQUIRE, "agent"); asm volatile("s_waitcnt vmcnt(0)" ::: "memory");
;     }
;     __syncthreads();
; }
.LBB0_340:
	s_setprio 0
	s_waitcnt vmcnt(0) lgkmcnt(0)
	s_barrier
	s_mov_b64 s[4:5], exec
	v_readlane_b32 s8, v242, 4
	v_readlane_b32 s9, v242, 5
	s_and_b64 s[8:9], s[4:5], s[8:9]
	s_mov_b64 exec, s[8:9]
	s_cbranch_execz .LBB0_366
	s_cmp_lg_u32 s92, 0x100
	s_cbranch_scc1 .Lseam2_orig
	buffer_wbl2 sc1
	s_waitcnt vmcnt(0)
	v_mov_b32_e32 v1, 0x8e02000
	v_mov_b32_e32 v2, 1
	global_atomic_add v2, v1, v2, s[90:91] sc0
	s_lshl_b32 s100, s2, 12
	s_add_u32 s100, s100, 0x8e10000
	v_mov_b32_e32 v1, s100
	s_waitcnt vmcnt(0)
	v_readfirstlane_b32 s100, v2
	s_cmp_eq_u32 s100, 0xff
	s_cbranch_scc0 .Lseam2_wait
	s_mov_b64 exec, -1
	v_mbcnt_lo_u32_b32 v243, -1, 0
	v_mbcnt_hi_u32_b32 v243, -1, v243
	v_lshlrev_b32_e32 v243, 12, v243
	v_add_u32_e32 v243, 0x8e10000, v243
	v_mov_b32_e32 v244, 2
	global_store_dword v243, v244, s[90:91] sc1
	v_add_u32_e32 v243, 0x40000, v243
	global_store_dword v243, v244, s[90:91] sc1
	v_add_u32_e32 v243, 0x40000, v243
	global_store_dword v243, v244, s[90:91] sc1
	v_add_u32_e32 v243, 0x40000, v243
	global_store_dword v243, v244, s[90:91] sc1
	s_mov_b64 exec, 1
	s_branch .Lseam2_done
